# attention unit: first K/V tiles of selected and window branches and third gate loaded at half start into free registers (no waits at use)
# speedup vs baseline: 1.0004x; 1.0004x over previous
; __device__ __forceinline__ float bf2f(unsigned short b) { return __uint_as_float(((unsigned)b) << 16); }
; __device__ __forceinline__ unsigned pk2(float lo, float hi) { return pg8::cvt_pk_bf16(lo, hi); }
; __device__ __forceinline__ float sigm(float x) { return __builtin_amdgcn_rcpf(1.0f + __expf(-x)); }
; __device__ __forceinline__ void nsa_mfma_phase(const bf16* z, const bf16* kch, const bf16* kcl, const bf16* vct, const bf16* vst, const bf16* vwt, const float* biasTab, bf16* oc,
;                                                LAS unsigned char* lds, int tid0, int vcu, int G) {
;     ...
;             lsum += __shfl_xor(lsum, 32);
;             const float g1 = sigm(bf2f(z[row * ZP + C_NG + 16 + head])) / lsum;
; #pragma unroll
;             for (int r = 0; r < 16; ++r) { tot[0][r] += o[0][r] * g1; tot[1][r] += o[1][r] * g1; }
;         }
;         {
;             f32x16 o[2]; float mrun = -INFINITY, lsum = 0.f;
; #pragma unroll
;             for (int r = 0; r < 16; ++r) { o[0][r] = 0.f; o[1][r] = 0.f; }
;             attn_branch<1>(z + (size_t)b * SEQ * ZP + C_KW + g * 64, vwt + (size_t)(b * 4 + g) * 64 * SEQ, qb >= 8 ? qb - 8 : 0, qb, qb, 0u, iq, qf, biasW, tb, o, mrun, lsum, tid, r32, hi_p);
;             lsum += __shfl_xor(lsum, 32);
;             const float g2 = sigm(bf2f(z[row * ZP + C_NG + 32 + head])) / lsum;
; #pragma unroll
;             for (int r = 0; r < 16; ++r) { tot[0][r] += o[0][r] * g2; tot[1][r] += o[1][r] * g2; }
;         }
;         { bf16* op = oc + row * 1024 + head * 64;
; #pragma unroll
;           for (int db = 0; db < 2; ++db)
; #pragma unroll
;               for (int a = 0; a < 4; ++a) { u32x2 w; w.x = pk2(tot[db][4 * a], tot[db][4 * a + 1]); w.y = pk2(tot[db][4 * a + 2], tot[db][4 * a + 3]);
;                   *(u32x2*)(op + 32 * db + 8 * a + 4 * hi_p) = w; } }
.LBB0_812:
	s_waitcnt vmcnt(0)
	v_lshlrev_b32_e32 v100, 16, v240
	v_mul_f32_e32 v100, 0xbfb8aa3b, v100
	v_lshlrev_b32_e32 v101, 16, v242
	v_exp_f32_e32 v100, v100
	v_mul_f32_e32 v101, 0xbfb8aa3b, v101
	v_exp_f32_e32 v102, v101
	v_add_f32_e32 v1, v1, v241
	v_add_f32_e32 v100, 1.0, v100
	v_rcp_f32_e32 v101, v100
	v_add_f32_e32 v100, 1.0, v102
	v_rcp_f32_e32 v100, v100
	v_lshlrev_b64 v[104:105], 11, v[164:165]
	v_mul_f32_e32 v102, v239, v101
	ds_bpermute_b32 v101, v238, v103
	v_div_scale_f32 v107, s[4:5], v1, v1, v100
	v_rcp_f32_e32 v108, v107
	v_div_scale_f32 v109, vcc, v100, v1, v100
	s_waitcnt lgkmcnt(0)
	v_add_f32_e32 v101, v103, v101
	v_fma_f32 v103, -v107, v108, 1.0
	v_fmac_f32_e32 v108, v103, v108
	v_mul_f32_e32 v103, v109, v108
	v_fma_f32 v110, -v107, v103, v109
	v_fmac_f32_e32 v103, v110, v108
	v_fma_f32 v107, -v107, v103, v109
	v_div_fmas_f32 v103, v107, v108, v103
	v_div_fixup_f32 v100, v103, v1, v100
	v_pk_mul_f32 v[36:37], v[36:37], v[100:101] op_sel_hi:[1,0]
	v_pk_mul_f32 v[38:39], v[38:39], v[100:101] op_sel_hi:[1,0]
	v_pk_fma_f32 v[20:21], v[20:21], v[102:103], v[36:37] op_sel_hi:[1,0,1]
	v_pk_fma_f32 v[22:23], v[22:23], v[102:103], v[38:39] op_sel_hi:[1,0,1]
	v_pk_mul_f32 v[40:41], v[40:41], v[100:101] op_sel_hi:[1,0]
	v_pk_mul_f32 v[52:53], v[52:53], v[100:101] op_sel_hi:[1,0]
	v_pk_fma_f32 v[24:25], v[24:25], v[102:103], v[40:41] op_sel_hi:[1,0,1]
	v_pk_mul_f32 v[54:55], v[54:55], v[100:101] op_sel_hi:[1,0]
	v_pk_mul_f32 v[56:57], v[56:57], v[100:101] op_sel_hi:[1,0]
	v_pk_mul_f32 v[58:59], v[58:59], v[100:101] op_sel_hi:[1,0]
	v_pk_mul_f32 v[60:61], v[60:61], v[100:101] op_sel_hi:[1,0]
	v_pk_mul_f32 v[44:45], v[44:45], v[100:101] op_sel_hi:[1,0]
	v_pk_mul_f32 v[62:63], v[62:63], v[100:101] op_sel_hi:[1,0]
	v_pk_mul_f32 v[46:47], v[46:47], v[100:101] op_sel_hi:[1,0]
	v_pk_mul_f32 v[64:65], v[64:65], v[100:101] op_sel_hi:[1,0]
	v_pk_mul_f32 v[66:67], v[66:67], v[100:101] op_sel_hi:[1,0]
	v_pk_fma_f32 v[4:5], v[4:5], v[102:103], v[52:53] op_sel_hi:[1,0,1]
	v_pk_fma_f32 v[6:7], v[6:7], v[102:103], v[54:55] op_sel_hi:[1,0,1]
	v_pk_mul_f32 v[42:43], v[42:43], v[100:101] op_sel_hi:[1,0]
	v_pk_mul_f32 v[48:49], v[48:49], v[100:101] op_sel_hi:[1,0]
	v_pk_mul_f32 v[50:51], v[50:51], v[100:101] op_sel_hi:[1,0]
	v_pk_fma_f32 v[8:9], v[8:9], v[102:103], v[56:57] op_sel_hi:[1,0,1]
	v_pk_fma_f32 v[10:11], v[10:11], v[102:103], v[58:59] op_sel_hi:[1,0,1]
	v_pk_fma_f32 v[12:13], v[12:13], v[102:103], v[60:61] op_sel_hi:[1,0,1]
	v_pk_fma_f32 v[28:29], v[28:29], v[102:103], v[44:45] op_sel_hi:[1,0,1]
	v_pk_fma_f32 v[14:15], v[14:15], v[102:103], v[62:63] op_sel_hi:[1,0,1]
	v_pk_fma_f32 v[30:31], v[30:31], v[102:103], v[46:47] op_sel_hi:[1,0,1]
	v_pk_fma_f32 v[16:17], v[16:17], v[102:103], v[64:65] op_sel_hi:[1,0,1]
	v_pk_fma_f32 v[18:19], v[18:19], v[102:103], v[66:67] op_sel_hi:[1,0,1]
	v_lshl_add_u64 v[104:105], v[162:163], 0, v[104:105]
	v_pk_fma_f32 v[26:27], v[26:27], v[102:103], v[42:43] op_sel_hi:[1,0,1]
	v_pk_fma_f32 v[32:33], v[32:33], v[102:103], v[48:49] op_sel_hi:[1,0,1]
	v_pk_fma_f32 v[34:35], v[34:35], v[102:103], v[50:51] op_sel_hi:[1,0,1]
	v_lshlrev_b32_e32 v1, 16, v251
	v_mul_f32_e32 v1, 0xbfb8aa3b, v1
	v_exp_f32_e32 v1, v1
	s_nop 0
	v_add_f32_e32 v1, 1.0, v1
	v_rcp_f32_e32 v1, v1
	s_nop 0
	v_div_scale_f32 v36, s[4:5], v101, v101, v1
	v_rcp_f32_e32 v37, v36
	v_div_scale_f32 v38, vcc, v1, v101, v1
	s_mov_b64 s[4:5], 0
	v_fma_f32 v39, -v36, v37, 1.0
	v_fmac_f32_e32 v37, v39, v37
	v_mul_f32_e32 v39, v38, v37
	v_fma_f32 v40, -v36, v39, v38
	v_fmac_f32_e32 v39, v40, v37
	v_fma_f32 v36, -v36, v39, v38
	v_div_fmas_f32 v36, v36, v37, v39
	v_div_fixup_f32 v36, v36, v101, v1
	v_pk_fma_f32 v[4:5], v[68:69], v[36:37], v[4:5] op_sel_hi:[1,0,1]
	v_pk_fma_f32 v[6:7], v[70:71], v[36:37], v[6:7] op_sel_hi:[1,0,1]
	v_pk_fma_f32 v[20:21], v[84:85], v[36:37], v[20:21] op_sel_hi:[1,0,1]
	v_pk_fma_f32 v[22:23], v[86:87], v[36:37], v[22:23] op_sel_hi:[1,0,1]
	v_pk_fma_f32 v[8:9], v[72:73], v[36:37], v[8:9] op_sel_hi:[1,0,1]
	v_pk_fma_f32 v[10:11], v[74:75], v[36:37], v[10:11] op_sel_hi:[1,0,1]
	v_pk_fma_f32 v[12:13], v[76:77], v[36:37], v[12:13] op_sel_hi:[1,0,1]
	v_pk_fma_f32 v[28:29], v[92:93], v[36:37], v[28:29] op_sel_hi:[1,0,1]
	v_pk_fma_f32 v[14:15], v[78:79], v[36:37], v[14:15] op_sel_hi:[1,0,1]
	v_pk_fma_f32 v[30:31], v[94:95], v[36:37], v[30:31] op_sel_hi:[1,0,1]
	v_pk_fma_f32 v[16:17], v[80:81], v[36:37], v[16:17] op_sel_hi:[1,0,1]
	v_pk_fma_f32 v[18:19], v[82:83], v[36:37], v[18:19] op_sel_hi:[1,0,1]
	v_cvt_pk_bf16_f32 v4, v4, v5
	v_cvt_pk_bf16_f32 v5, v6, v7
	v_pk_fma_f32 v[24:25], v[88:89], v[36:37], v[24:25] op_sel_hi:[1,0,1]
	v_pk_fma_f32 v[26:27], v[90:91], v[36:37], v[26:27] op_sel_hi:[1,0,1]
	v_pk_fma_f32 v[32:33], v[96:97], v[36:37], v[32:33] op_sel_hi:[1,0,1]
	v_pk_fma_f32 v[34:35], v[98:99], v[36:37], v[34:35] op_sel_hi:[1,0,1]
	v_cvt_pk_bf16_f32 v6, v8, v9
	v_cvt_pk_bf16_f32 v7, v10, v11
	v_cvt_pk_bf16_f32 v8, v12, v13
	v_cvt_pk_bf16_f32 v9, v14, v15
	v_cvt_pk_bf16_f32 v10, v16, v17
	v_cvt_pk_bf16_f32 v11, v18, v19
	v_cvt_pk_bf16_f32 v12, v20, v21
	v_cvt_pk_bf16_f32 v13, v22, v23
	global_store_dwordx2 v[104:105], v[4:5], off
	global_store_dwordx2 v[104:105], v[6:7], off offset:16
	global_store_dwordx2 v[104:105], v[8:9], off offset:32
	global_store_dwordx2 v[104:105], v[10:11], off offset:48
	global_store_dwordx2 v[104:105], v[12:13], off offset:64
	v_cvt_pk_bf16_f32 v4, v28, v29
	v_cvt_pk_bf16_f32 v5, v30, v31
	v_cvt_pk_bf16_f32 v14, v24, v25
	v_cvt_pk_bf16_f32 v15, v26, v27
	global_store_dwordx2 v[104:105], v[4:5], off offset:96
	v_cvt_pk_bf16_f32 v4, v32, v33
	v_cvt_pk_bf16_f32 v5, v34, v35
	s_and_b64 vcc, exec, s[34:35]
	global_store_dwordx2 v[104:105], v[14:15], off offset:80
	global_store_dwordx2 v[104:105], v[4:5], off offset:112
	s_cbranch_vccnz .LBB0_810
; #define LAS __attribute__((address_space(3)))
; template <int MODE> ...
;     ...
;     { const u32x4 kw = tile_ld(kbase + (size_t)jlo * 64 * ZP, ZP, tid), vw = tile_ld(vtbase + jlo * 64, SEQ, tid); tile_st(tb, kw, tid); tile_st(tb + TILEB, vw, tid); }
; __device__ __forceinline__ void nsa_mfma_phase(const bf16* z, const bf16* kch, const bf16* kcl, const bf16* vct, const bf16* vst, const bf16* vwt, const float* biasTab, bf16* oc,
;                                                LAS unsigned char* lds, int tid0, int vcu, int G) {
;     ...
;         const int bg = p0 >> 4, b = bg >> 2, g = bg & 3, qb = half ? 31 - (p0 & 15) : (p0 & 15);
;         int r32 = r32_p; asm volatile("" : "+v"(r32));
;         const int iq = 32 * ts + r32, t = 64 * qb + iq, head = g * 4 + hh; const size_t row = (size_t)b * SEQ + t;
;         const LAS float* biasW = biasL + head * 256;
;         bf16x8 qf[4];
; #pragma unroll
;         for (int d0 = 0; d0 < 4; ++d0) qf[d0] = *(const bf16x8*)(z + row * ZP + C_NQ + head * 64 + d0 * 16 + hi_p * 8);
.LBB0_813:
	s_xor_b64 s[34:35], s[4:5], -1
	s_and_b64 s[4:5], s[4:5], exec
	s_cselect_b32 s48, s54, s55
	v_mov_b32_e32 v10, v159
	s_lshl_b32 s51, s48, 6
	v_add_u32_e32 v236, s43, v10
	v_add_u32_e32 v4, s51, v236
	v_ashrrev_i32_e32 v5, 31, v4
	v_lshl_add_u64 v[164:165], s[6:7], 0, v[4:5]
	v_mov_b64_e32 v[6:7], s[76:77]
	v_mad_u64_u32 v[166:167], s[4:5], v164, s88, v[6:7]
	v_mad_i32_i24 v167, v165, s88, v167
	v_lshl_add_u64 v[6:7], v[166:167], 0, s[68:69]
	v_lshl_add_u64 v[6:7], v[6:7], 0, v[2:3]
	v_lshl_add_u64 v[8:9], v[6:7], 0, s[66:67]
	v_add_co_u32_e32 v6, vcc, s75, v6
	v_mov_b32_e32 v1, v158
	s_nop 0
	v_addc_co_u32_e32 v7, vcc, 0, v7, vcc
	global_load_dwordx4 v[134:137], v[8:9], off offset:32
	global_load_dwordx4 v[138:141], v[8:9], off offset:64
	global_load_dwordx4 v[142:145], v[6:7], off offset:1024
	global_load_dwordx4 v[146:149], v[8:9], off offset:96
	v_ashrrev_i32_e32 v202, 3, v158
	v_lshlrev_b32_e32 v204, 4, v158
	v_ashrrev_i32_e32 v203, 31, v202
	v_and_b32_e32 v204, 0x70, v204
	v_mov_b32_e32 v205, v3
	v_lshlrev_b64 v[206:207], 12, v[202:203]
	v_mad_i64_i32 v[208:209], s[4:5], v202, s88, v[204:205]
	v_or_b32_e32 v206, v206, v204
	s_max_i32 vcc_lo, s48, 8
	s_add_i32 vcc_lo, vcc_lo, -8
	v_lshl_add_u64 v[210:211], s[20:21], 0, v[208:209]
	global_load_dwordx4 v[186:189], v[210:211], off
	v_lshl_add_u64 v[210:211], s[22:23], 0, v[206:207]
	global_load_dwordx4 v[190:193], v[210:211], off
	s_mul_i32 s4, vcc_lo, 0x168000
	s_mov_b32 s5, 0
	v_lshl_add_u64 v[208:209], s[46:47], 0, v[208:209]
	v_lshl_add_u64 v[206:207], s[44:45], 0, v[206:207]
	v_lshl_add_u64 v[208:209], v[208:209], 0, s[4:5]
	s_lshl_b32 s4, vcc_lo, 7
	global_load_dwordx4 v[194:197], v[208:209], off
	v_lshl_add_u64 v[206:207], v[206:207], 0, s[4:5]
	s_lshl_b32 s36, s56, 1
	s_mov_b32 s37, s69
	global_load_dwordx4 v[198:201], v[206:207], off
	v_lshl_add_u64 v[210:211], v[166:167], 0, s[36:37]
	v_add_co_u32_e32 v210, vcc, 0x5000, v210
	s_nop 1
	v_addc_co_u32_e32 v211, vcc, 0, v211, vcc
	global_load_ushort v251, v[210:211], off offset:2112
	s_cmp_gt_u32 s48, 15
	s_cselect_b64 s[14:15], -1, 0
	v_ashrrev_i32_e32 v68, 3, v1
	v_ashrrev_i32_e32 v69, 31, v68
	v_lshlrev_b32_e32 v6, 4, v1
	s_and_b64 s[4:5], s[14:15], exec
	v_and_b32_e32 v11, 0x70, v6
	v_lshlrev_b64 v[8:9], 8, v[68:69]
	v_lshlrev_b64 v[6:7], 7, v[68:69]
	s_cselect_b32 s16, 2, 1
	v_mul_lo_u32 v5, v68, s87
	v_or_b32_e32 v6, v6, v11
	v_or_b32_e32 v8, v8, v11
	v_add3_u32 v5, 0, v5, v11
	v_lshl_add_u64 v[6:7], s[24:25], 0, v[6:7]
	v_lshl_add_u64 v[8:9], s[26:27], 0, v[8:9]
	s_mov_b32 s4, s16

; template <int MODE> ...
;     ...
;     { const u32x4 kw = tile_ld(kbase + (size_t)jlo * 64 * ZP, ZP, tid), vw = tile_ld(vtbase + jlo * 64, SEQ, tid); tile_st(tb, kw, tid); tile_st(tb + TILEB, vw, tid); }
;     __syncthreads();
;     const float b31 = biasW[64 + 127];
; __device__ __forceinline__ void nsa_mfma_phase(const bf16* z, const bf16* kch, const bf16* kcl, const bf16* vct, const bf16* vst, const bf16* vwt, const float* biasTab, bf16* oc,
;                                                LAS unsigned char* lds, int tid0, int vcu, int G) {
;     ...
;             f32x16 o[2]; float mrun = -INFINITY, lsum = 0.f;
; #pragma unroll
;             for (int r = 0; r < 16; ++r) { o[0][r] = 0.f; o[1][r] = 0.f; }
;             attn_branch<0>(z + (size_t)b * SEQ * ZP + C_KS + g * 64, vst + (size_t)(b * 4 + g) * 64 * SEQ, 0, qb, qb, selmask, iq, qf, biasW, tb, o, mrun, lsum, tid, r32, hi_p);
.LBB0_841:
	v_mov_b32_e32 v1, v158
	s_barrier
	v_mov_b64_e32 v[36:37], s[20:21]
	v_ashrrev_i32_e32 v44, 3, v1
	v_ashrrev_i32_e32 v45, 31, v44
	v_lshlrev_b32_e32 v1, 4, v1
	v_mad_i64_i32 v[36:37], s[4:5], v44, s88, v[36:37]
	v_and_b32_e32 v48, 0x70, v1
	v_mov_b32_e32 v49, v3
	v_lshlrev_b64 v[50:51], 12, v[44:45]
	v_mul_lo_u32 v1, v44, s87
	v_add3_u32 v157, 0, v1, v48
	v_mov_b32_e32 v1, s57
	v_mad_i64_i32 v[46:47], s[4:5], v44, s88, 0
	v_or_b32_e32 v50, v50, v48
	v_or_b32_e32 v46, v46, v48
	v_mov_b32_e32 v169, 0
	v_lshl_add_u64 v[108:109], s[28:29], 0, v[50:51]
	v_lshl_add_u64 v[110:111], s[30:31], 0, v[46:47]
	s_mov_b32 s14, 0
	v_mov_b32_e32 v170, 0xff800000
	s_mov_b32 s15, s48
	v_mov_b32_e32 v44, v169
	v_mov_b32_e32 v45, v169
	v_mov_b32_e32 v46, v169
	v_mov_b32_e32 v47, v169
	v_mov_b32_e32 v48, v169
	v_mov_b32_e32 v49, v169
	v_mov_b32_e32 v50, v169
	v_mov_b32_e32 v51, v169
	v_mov_b32_e32 v52, 0
	v_mov_b32_e32 v53, v169
	v_mov_b32_e32 v54, v169
	v_mov_b32_e32 v55, v169
	v_mov_b32_e32 v56, v169
	v_mov_b32_e32 v57, v169
	v_mov_b32_e32 v58, v169
	v_mov_b32_e32 v59, v169
	v_mov_b32_e32 v60, v169
	v_mov_b32_e32 v61, v169
	v_mov_b32_e32 v62, v169
	v_mov_b32_e32 v63, v169
	v_mov_b32_e32 v64, v169
	v_mov_b32_e32 v65, v169
	v_mov_b32_e32 v66, v169
	v_mov_b32_e32 v67, v169
	ds_write_b128 v157, v[186:189]
	ds_write_b128 v157, v[190:193] offset:9216
	s_waitcnt lgkmcnt(0)
	s_barrier
	ds_read_b32 v168, v1 offset:56060
	v_mov_b32_e32 v36, 0
	v_mov_b32_e32 v37, v169
	v_mov_b32_e32 v38, v169
	v_mov_b32_e32 v39, v169
	v_mov_b32_e32 v40, v169
	v_mov_b32_e32 v41, v169
	v_mov_b32_e32 v42, v169
	v_mov_b32_e32 v43, v169
	s_cmp_lt_u32 s14, s48
	s_cselect_b64 s[10:11], -1, 0
	s_cmp_ge_u32 s14, s48
	s_cbranch_scc1 .LBB0_844
	s_branch .LBB0_843

; __device__ __forceinline__ void softmax_pv(f32x16& s0, f32x16& s1, float& mrun, float& lsum, f32x16 (&o)[2], const LAS unsigned char* Vt, int r32, int hi) {
;     ...
;     for (int r = 0; r < 16; r += 2) {
;         f32x2v d0 = (f32x2v){s0[r], s0[r + 1]} - mm, d1 = (f32x2v){s1[r], s1[r + 1]} - mm;
;         s0[r] = __builtin_amdgcn_exp2f(d0[0]); s0[r + 1] = __builtin_amdgcn_exp2f(d0[1]); s1[r] = __builtin_amdgcn_exp2f(d1[0]); s1[r + 1] = __builtin_amdgcn_exp2f(d1[1]);
;         ps2 += (f32x2v){s0[r], s0[r + 1]}; ps2 += (f32x2v){s1[r], s1[r + 1]}; }
;     lsum = lsum * alpha + (ps2[0] + ps2[1]); mrun = mnew;
; __device__ __forceinline__ void nsa_mfma_phase(const bf16* z, const bf16* kch, const bf16* kcl, const bf16* vct, const bf16* vst, const bf16* vwt, const float* biasTab, bf16* oc,
;                                                LAS unsigned char* lds, int tid0, int vcu, int G) {
;     ...
;             f32x16 o[2]; float mrun = -INFINITY, lsum = 0.f;
; #pragma unroll
;             for (int r = 0; r < 16; ++r) { o[0][r] = 0.f; o[1][r] = 0.f; }
;             attn_branch<1>(z + (size_t)b * SEQ * ZP + C_KW + g * 64, vwt + (size_t)(b * 4 + g) * 64 * SEQ, qb >= 8 ? qb - 8 : 0, qb, qb, 0u, iq, qf, biasW, tb, o, mrun, lsum, tid, r32, hi_p);
.LBB0_852:
	v_pk_add_f32 v[68:69], v[68:69], 0 op_sel_hi:[1,0]
	s_add_i32 s14, s14, 1
	v_pk_add_f32 v[68:69], v[70:71], v[68:69]
	s_sub_i32 s51, s51, 64
	v_pk_add_f32 v[68:69], v[68:69], v[72:73]
	s_add_i32 s15, s15, -1
	v_pk_add_f32 v[68:69], v[74:75], v[68:69]
	v_lshl_add_u64 v[108:109], v[108:109], 0, s[70:71]
	v_pk_add_f32 v[68:69], v[68:69], v[76:77]
	s_cmpk_lg_i32 s51, 0xffc0
	v_pk_add_f32 v[68:69], v[78:79], v[68:69]
	v_lshl_add_u64 v[110:111], v[110:111], 0, s[84:85]
	v_pk_add_f32 v[68:69], v[68:69], v[80:81]
	s_waitcnt lgkmcnt(0)
	v_pk_add_f32 v[68:69], v[82:83], v[68:69]
	s_barrier
	v_pk_add_f32 v[68:69], v[68:69], v[84:85]
	s_nop 0
	v_pk_add_f32 v[68:69], v[86:87], v[68:69]
	s_nop 0
	v_pk_add_f32 v[68:69], v[68:69], v[88:89]
	s_nop 0
	v_pk_add_f32 v[68:69], v[90:91], v[68:69]
	s_nop 0
	v_pk_add_f32 v[68:69], v[68:69], v[92:93]
	s_nop 0
	v_pk_add_f32 v[68:69], v[94:95], v[68:69]
	s_nop 0
	v_pk_add_f32 v[68:69], v[68:69], v[96:97]
	s_nop 0
	v_pk_add_f32 v[68:69], v[98:99], v[68:69]
	s_nop 0
	v_add_f32_e32 v1, v68, v69
	v_fmac_f32_e32 v1, v169, v112
	s_cbranch_scc1 .LBB0_842
	s_max_i32 s12, s48, 8
	s_mov_b32 s37, s69
	s_add_i32 s10, s12, -8
	v_lshl_add_u64 v[68:69], v[166:167], 0, s[36:37]
	s_mul_i32 s4, s10, 0x168000
	v_add_co_u32_e32 v68, vcc, 0x5000, v68
	s_mul_hi_u32 s5, s10, 0x168000
	s_add_u32 s4, s46, s4
	v_addc_co_u32_e32 v69, vcc, 0, v69, vcc
	v_mov_b32_e32 v70, v158
	s_addc_u32 s5, s47, s5
	global_load_ushort v242, v[68:69], off offset:2080
	v_mov_b64_e32 v[68:69], s[4:5]
	s_waitcnt vmcnt(2)
	v_ashrrev_i32_e32 v102, 3, v70
	v_mad_i64_i32 v[68:69], s[4:5], v102, s88, v[68:69]
	s_lshl_b32 s4, s10, 7
	v_ashrrev_i32_e32 v103, 31, v102
	v_lshlrev_b32_e32 v70, 4, v70
	s_add_u32 s4, s44, s4
	s_waitcnt vmcnt(1)
	v_and_b32_e32 v104, 0x70, v70
	v_mov_b32_e32 v105, v3
	s_addc_u32 s5, s45, 0
	v_lshlrev_b64 v[106:107], 12, v[102:103]
	v_lshl_add_u64 v[68:69], v[68:69], 0, v[104:105]
	v_lshl_add_u64 v[72:73], s[4:5], 0, v[106:107]
	ds_bpermute_b32 v241, v238, v1
	v_mul_lo_u32 v76, v102, s87
	v_add3_u32 v243, 0, v76, v104
	v_mov_b32_e32 v83, 0
	s_cmp_gt_i32 s10, s48
	v_mov_b32_e32 v82, v83
	v_mov_b32_e32 v81, v83
	v_mov_b32_e32 v80, v83
	v_mov_b32_e32 v79, v83
	v_mov_b32_e32 v78, v83
	v_mov_b32_e32 v77, v83
	v_mov_b32_e32 v76, v83
	v_mov_b32_e32 v99, v83
	v_mov_b32_e32 v98, v83
	v_mov_b32_e32 v97, v83
	v_mov_b32_e32 v96, v83
	v_mov_b32_e32 v95, v83
	v_mov_b32_e32 v94, v83
	v_mov_b32_e32 v93, v83
	v_mov_b32_e32 v92, v83
	v_mov_b32_e32 v91, v83
	v_mov_b32_e32 v90, v83
	v_mov_b32_e32 v89, v83
	v_mov_b32_e32 v88, v83
	v_mov_b32_e32 v87, v83
	v_mov_b32_e32 v86, v83
	v_mov_b32_e32 v85, v83
	v_mov_b32_e32 v84, v83
	v_mov_b32_e32 v103, v83
	ds_write_b128 v243, v[194:197]
	ds_write_b128 v243, v[198:201] offset:9216
	v_mov_b32_e32 v75, v83
	v_mov_b32_e32 v74, v83
	v_mov_b32_e32 v73, v83
	v_mov_b32_e32 v72, v83
	v_mov_b32_e32 v71, v83
	v_mov_b32_e32 v70, v83
	v_mov_b32_e32 v69, v83
	v_mov_b32_e32 v68, v83
	s_waitcnt lgkmcnt(0)
	s_barrier
	s_cbranch_scc1 .LBB0_812
	s_lshl_b32 s4, s12, 7
	s_addk_i32 s4, 0xfc80
	s_add_u32 s4, s44, s4
	v_mov_b32_e32 v68, s57
	v_or_b32_e32 v106, v106, v104
	s_addc_u32 s5, s45, 0
	ds_read_b32 v100, v68 offset:56060
	v_lshl_add_u64 v[168:169], s[4:5], 0, v[106:107]
	v_mad_i64_i32 v[68:69], s[4:5], v102, s88, 0
	s_mul_i32 s4, s12, 0x168000
	s_add_i32 s4, s4, 0xff628000
	s_add_u32 s4, s0, s4
	s_addc_u32 s5, s1, 0
	s_sub_i32 s13, s48, s12
	v_or_b32_e32 v68, v68, v104
	s_add_i32 s15, s13, 8
	v_mov_b32_e32 v244, 0
	v_lshl_add_u64 v[170:171], s[4:5], 0, v[68:69]
	s_mov_b32 s14, 8
	s_lshl_b32 s16, s15, 6
	v_mov_b32_e32 v245, 0xff800000
	s_mov_b32 s17, 0
	s_waitcnt lgkmcnt(0)
	v_mov_b32_e32 v101, v100
	v_mov_b32_e32 v84, 0
	v_mov_b32_e32 v85, v244
	v_mov_b32_e32 v86, v244
	v_mov_b32_e32 v87, v244
	v_mov_b32_e32 v88, v244
	v_mov_b32_e32 v89, v244
	v_mov_b32_e32 v90, v244
	v_mov_b32_e32 v91, v244
	v_mov_b32_e32 v92, v244
	v_mov_b32_e32 v93, v244
	v_mov_b32_e32 v94, v244
	v_mov_b32_e32 v95, v244
	v_mov_b32_e32 v96, v244
	v_mov_b32_e32 v97, v244
	v_mov_b32_e32 v98, v244
	v_mov_b32_e32 v99, v244
	v_mov_b32_e32 v68, 0
	v_mov_b32_e32 v69, v244
	v_mov_b32_e32 v70, v244
	v_mov_b32_e32 v71, v244
	v_mov_b32_e32 v72, v244
	v_mov_b32_e32 v73, v244
	v_mov_b32_e32 v74, v244
	v_mov_b32_e32 v75, v244
	v_mov_b32_e32 v76, v244
	v_mov_b32_e32 v77, v244
	v_mov_b32_e32 v78, v244
	v_mov_b32_e32 v79, v244
	v_mov_b32_e32 v80, v244
	v_mov_b32_e32 v81, v244
	v_mov_b32_e32 v82, v244
	v_mov_b32_e32 v83, v244
